# NSA top-16 ranking loop rewritten by hand: integer-order compare + add-carry per block, in-lane tie terms precomputed (same selection rule)
# speedup vs baseline: 1.0134x; 1.0134x over previous
; DI int tid_now() { int t = threadIdx.x; asm volatile("" : "+v"(t)); return t; }
; #define PG8_LAS __attribute__((address_space(3)))
;     DI bf16_t* q() const { return (bf16_t*)(ws + WS_Q); }
; DI void unit_nsa(Frame& F, int b, int g, int qt, int tid) {
;     ...
;     { const int tid = tid_now();
;         PG8_LAS float* ib = (PG8_LAS float*)(F.ldsp + A_IMP);
;         const int q = tid >> 3, jj = tid & 7;
;         float mine[8];
; #pragma unroll
;         for (int k = 0; k < 8; ++k) { const int j = 8 * jj + k; const int o = q * A_IMPLD + j;
;             float v = ((ib[o] * ilq[q] + ib[64 * A_IMPLD + o] * ilq[64 + q]) + ib[2 * 64 * A_IMPLD + o] * ilq[128 + q]) + ib[3 * 64 * A_IMPLD + o] * ilq[192 + q];
;             if (j > qt) v = -INFINITY; if (j == 0 || j == qt || j == qt - 1) v = INFINITY; mine[k] = v; }
;         __syncthreads();
.LBB0_1374:
	v_div_scale_f32 v0, s[16:17], v120, v120, 1.0
	s_waitcnt vmcnt(0)
	v_rcp_f32_e32 v2, v0
	v_div_scale_f32 v3, vcc, 1.0, v120, 1.0
	v_fma_f32 v4, -v0, v2, 1.0
	v_fmac_f32_e32 v2, v4, v2
	v_mul_f32_e32 v4, v3, v2
	v_fma_f32 v5, -v0, v4, v3
	v_fmac_f32_e32 v4, v5, v2
	v_fma_f32 v0, -v0, v4, v3
	v_div_fmas_f32 v0, v0, v2, v4
	v_div_fixup_f32 v0, v0, v120, 1.0
	v_cmp_lt_f32_e32 vcc, 0, v120
	s_nop 1
	v_cndmask_b32_e32 v208, 0, v0, vcc
	v_cmp_eq_u32_e32 vcc, 0, v108
	s_and_saveexec_b64 s[16:17], vcc
	v_lshl_add_u32 v0, v109, 2, 0
	v_add_u32_e32 v0, 0x1b610, v0
	ds_write_b32 v0, v208
	s_or_b64 exec, exec, s[16:17]
	s_waitcnt lgkmcnt(0)
	s_barrier
	v_mov_b32_e32 v76, v214
	s_movk_i32 s16, 0x104
	v_ashrrev_i32_e32 v0, 3, v76
	v_mul_lo_u32 v2, v0, s16
	v_and_b32_e32 v78, 7, v76
	v_add_u32_e32 v79, 0, v2
	v_lshl_add_u32 v0, v0, 2, 0
	v_lshl_add_u32 v51, v78, 5, v79
	v_add_u32_e32 v0, 0x1b610, v0
	v_add_u32_e32 v53, 0xb000, v51
	ds_read2st64_b32 v[14:15], v0 offset1:1
	ds_read2st64_b32 v[48:49], v0 offset0:2 offset1:3
	v_add_u32_e32 v2, 0xf100, v51
	v_add_u32_e32 v4, 0x8200, v53
	v_add_u32_e32 v6, 0xc300, v53
	ds_read2_b32 v[2:3], v2 offset1:1
	ds_read2_b32 v[4:5], v4 offset1:1
	ds_read2_b32 v[6:7], v6 offset1:1
	ds_read2_b32 v[8:9], v53 offset1:1
	s_waitcnt lgkmcnt(5)
	v_mov_b32_e32 v50, v15
	s_waitcnt lgkmcnt(3)
	v_pk_mul_f32 v[2:3], v[50:51], v[2:3] op_sel_hi:[0,1]
	v_lshlrev_b32_e32 v0, 3, v78
	s_sub_i32 s22, 62, s97
	s_waitcnt lgkmcnt(0)
	v_pk_fma_f32 v[2:3], v[14:15], v[8:9], v[2:3] op_sel_hi:[0,1,1]
	v_pk_fma_f32 v[2:3], v[48:49], v[4:5], v[2:3] op_sel_hi:[0,1,1]
	v_or_b32_e32 v4, 2, v0
	v_lshl_add_u32 v5, v4, 2, v79
	v_cmp_eq_u32_e64 s[46:47], 0, v78
	v_cmp_eq_u32_e32 vcc, s92, v0
	v_or_b32_e32 v10, 1, v0
	v_add_u32_e32 v12, 0xb000, v5
	s_or_b64 s[16:17], s[46:47], vcc
	v_mov_b32_e32 v52, v49
	v_cmp_eq_u32_e32 vcc, s92, v10
	v_cmp_eq_u32_e64 s[52:53], s22, v10
	v_add_u32_e32 v5, 0xf100, v5
	v_add_u32_e32 v8, 0x8200, v12
	v_add_u32_e32 v10, 0xc300, v12
	v_pk_fma_f32 v[2:3], v[52:53], v[6:7], v[2:3] op_sel_hi:[0,1,1]
	ds_read2_b32 v[6:7], v5 offset1:1
	ds_read2_b32 v[8:9], v8 offset1:1
	ds_read2_b32 v[10:11], v10 offset1:1
	ds_read2_b32 v[12:13], v12 offset1:1
	v_cmp_gt_u32_e64 s[48:49], s92, v0
	s_waitcnt lgkmcnt(3)
	v_pk_mul_f32 v[6:7], v[50:51], v[6:7] op_sel_hi:[0,1]
	v_cmp_ge_u32_e64 s[50:51], s92, v0
	v_cmp_eq_u32_e64 s[54:55], s22, v0
	v_add_u32_e32 v49, 0xb008, v51
	s_waitcnt lgkmcnt(0)
	v_pk_fma_f32 v[6:7], v[14:15], v[12:13], v[6:7] op_sel_hi:[0,1,1]
	v_cndmask_b32_e64 v3, v225, v3, s[48:49]
	v_cndmask_b32_e64 v2, v225, v2, s[50:51]
	s_or_b64 s[54:55], s[16:17], s[54:55]
	s_or_b64 vcc, vcc, s[52:53]
	v_or_b32_e32 v5, 3, v0
	v_pk_fma_f32 v[6:7], v[48:49], v[8:9], v[6:7] op_sel_hi:[0,1,1]
	v_cndmask_b32_e64 v2, v2, v222, s[54:55]
	v_cndmask_b32_e32 v3, v3, v222, vcc
	v_pk_fma_f32 v[6:7], v[52:53], v[10:11], v[6:7] op_sel_hi:[0,1,1]
	v_cmp_lt_u32_e64 s[54:55], s92, v4
	v_cmp_lt_u32_e64 s[52:53], s92, v5
	v_cmp_eq_u32_e32 vcc, s92, v5
	v_cmp_eq_u32_e64 s[58:59], s22, v5
	v_cndmask_b32_e64 v8, v6, v225, s[54:55]
	v_cndmask_b32_e64 v6, v7, v225, s[52:53]
	s_or_b64 vcc, vcc, s[58:59]
	v_cndmask_b32_e32 v7, v6, v222, vcc
	v_or_b32_e32 v6, 4, v0
	v_lshl_add_u32 v9, v6, 2, v79
	v_add_u32_e32 v15, 0xb000, v9
	v_add_u32_e32 v9, 0xf100, v9
	v_add_u32_e32 v12, 0x8200, v15
	v_add_u32_e32 v54, 0xc300, v15
	ds_read2_b32 v[10:11], v9 offset1:1
	ds_read2_b32 v[12:13], v12 offset1:1
	ds_read2_b32 v[54:55], v54 offset1:1
	ds_read2_b32 v[56:57], v15 offset1:1
	v_cmp_eq_u32_e64 s[56:57], s92, v4
	s_waitcnt lgkmcnt(3)
	v_pk_mul_f32 v[10:11], v[50:51], v[10:11] op_sel_hi:[0,1]
	v_cmp_eq_u32_e64 s[60:61], s22, v4
	s_or_b64 vcc, s[56:57], s[60:61]
	s_waitcnt lgkmcnt(0)
	v_pk_fma_f32 v[10:11], v[14:15], v[56:57], v[10:11] op_sel_hi:[0,1,1]
	v_or_b32_e32 v9, 5, v0
	v_pk_fma_f32 v[10:11], v[48:49], v[12:13], v[10:11] op_sel_hi:[0,1,1]
	v_cndmask_b32_e32 v8, v8, v222, vcc
	v_pk_fma_f32 v[10:11], v[52:53], v[54:55], v[10:11] op_sel_hi:[0,1,1]
	v_cmp_lt_u32_e64 s[58:59], s92, v6
	v_cmp_lt_u32_e64 s[56:57], s92, v9
	v_cmp_eq_u32_e32 vcc, s92, v9
	v_cmp_eq_u32_e64 s[62:63], s22, v9
	v_cndmask_b32_e64 v12, v10, v225, s[58:59]
	v_cndmask_b32_e64 v10, v11, v225, s[56:57]
	s_or_b64 vcc, vcc, s[62:63]
	v_cndmask_b32_e32 v11, v10, v222, vcc
	v_or_b32_e32 v10, 6, v0
	v_lshl_add_u32 v13, v10, 2, v79
	v_add_u32_e32 v15, 0xb000, v13
	v_add_u32_e32 v13, 0xf100, v13
	v_add_u32_e32 v56, 0x8200, v15
	v_add_u32_e32 v58, 0xc300, v15
	ds_read2_b32 v[54:55], v13 offset1:1
	ds_read2_b32 v[56:57], v56 offset1:1
	ds_read2_b32 v[58:59], v58 offset1:1
	ds_read2_b32 v[60:61], v15 offset1:1
	v_add_u32_e32 v62, 0xb010, v51
	v_add_u32_e32 v63, 0xb018, v51
	s_waitcnt lgkmcnt(3)
	v_pk_mul_f32 v[50:51], v[50:51], v[54:55] op_sel_hi:[0,1]
	v_cmp_eq_u32_e64 s[60:61], s92, v6
	v_cmp_eq_u32_e64 s[64:65], s22, v6
	s_waitcnt lgkmcnt(0)
	v_pk_fma_f32 v[14:15], v[14:15], v[60:61], v[50:51] op_sel_hi:[0,1,1]
	s_or_b64 vcc, s[60:61], s[64:65]
	v_or_b32_e32 v13, 7, v0
	v_pk_fma_f32 v[14:15], v[48:49], v[56:57], v[14:15] op_sel_hi:[0,1,1]
	v_cndmask_b32_e32 v12, v12, v222, vcc
	v_pk_fma_f32 v[14:15], v[52:53], v[58:59], v[14:15] op_sel_hi:[0,1,1]
	v_cmp_lt_u32_e64 s[60:61], s92, v13
	v_cmp_eq_u32_e32 vcc, s92, v13
	v_cmp_eq_u32_e64 s[66:67], s22, v13
	v_cmp_lt_u32_e64 s[62:63], s92, v10
	v_cndmask_b32_e64 v15, v15, v225, s[60:61]
	v_cmp_eq_u32_e64 s[64:65], s92, v10
	v_cmp_eq_u32_e64 s[68:69], s22, v10
	s_or_b64 vcc, vcc, s[66:67]
	v_cndmask_b32_e64 v14, v14, v225, s[62:63]
	v_cndmask_b32_e32 v15, v15, v222, vcc
	s_or_b64 vcc, s[64:65], s[68:69]
	v_cndmask_b32_e32 v14, v14, v222, vcc
	s_barrier
;     DI bf16_t* q() const { return (bf16_t*)(ws + WS_Q); }
; DI void unit_nsa(Frame& F, int b, int g, int qt, int tid) {
;     ...
; #pragma unroll
;         for (int k = 0; k < 8; ++k) ib[q * A_IMPLD + 8 * jj + k] = mine[k];
;         __syncthreads();
;         int rank[8];
; #pragma unroll
;         for (int k = 0; k < 8; ++k) rank[k] = 0;
;         float vnx = ib[q * A_IMPLD];
;         for (int j2 = 0; j2 <= qt; ++j2) { const float v2 = vnx; vnx = ib[q * A_IMPLD + (j2 < qt ? j2 + 1 : j2)];
; #pragma unroll
;             for (int k = 0; k < 8; ++k) rank[k] += (v2 > mine[k] || (v2 == mine[k] && j2 < 8 * jj + k)) ? 1 : 0; }
;         unsigned bits = 0u;
; #pragma unroll
;         for (int k = 0; k < 8; ++k) if (rank[k] < 16 && 8 * jj + k <= qt) bits |= 1u << k;
	ds_write2_b32 v53, v2, v3 offset1:1
	ds_write2_b32 v49, v8, v7 offset1:1
	ds_write2_b32 v62, v12, v11 offset1:1
	ds_write2_b32 v63, v14, v15 offset1:1
	s_waitcnt lgkmcnt(0)
	s_barrier
	ds_read_b32 v80, v79 offset:45056
	s_sub_i32 s22, 64, s97
	s_mov_b32 s23, 0
	v_mov_b32_e32 v55, 0
	v_mov_b32_e32 v54, 0
	v_mov_b32_e32 v53, 0
	v_mov_b32_e32 v52, 0
	v_mov_b32_e32 v51, 0
	v_mov_b32_e32 v50, 0
	v_mov_b32_e32 v49, 0
	v_mov_b32_e32 v48, 0
	v_cmp_eq_u32_e64 s[16:17], v2, v3
	v_cmp_eq_u32_e64 s[24:25], v2, v8
	v_cmp_eq_u32_e64 s[68:69], v3, v8
	v_cmp_eq_u32_e32 vcc, v2, v7
	v_addc_co_u32_e64 v54, s[16:17], 0, v54, s[16:17]
	v_addc_co_u32_e64 v53, s[24:25], 0, v53, s[24:25]
	v_addc_co_u32_e64 v53, s[68:69], 0, v53, s[68:69]
	v_addc_co_u32_e32 v52, vcc, 0, v52, vcc
	v_cmp_eq_u32_e64 s[16:17], v3, v7
	v_cmp_eq_u32_e64 s[24:25], v8, v7
	v_cmp_eq_u32_e64 s[68:69], v2, v12
	v_cmp_eq_u32_e32 vcc, v3, v12
	v_addc_co_u32_e64 v52, s[16:17], 0, v52, s[16:17]
	v_addc_co_u32_e64 v52, s[24:25], 0, v52, s[24:25]
	v_addc_co_u32_e64 v51, s[68:69], 0, v51, s[68:69]
	v_addc_co_u32_e32 v51, vcc, 0, v51, vcc
	v_cmp_eq_u32_e64 s[16:17], v8, v12
	v_cmp_eq_u32_e64 s[24:25], v7, v12
	v_cmp_eq_u32_e64 s[68:69], v2, v11
	v_cmp_eq_u32_e32 vcc, v3, v11
	v_addc_co_u32_e64 v51, s[16:17], 0, v51, s[16:17]
	v_addc_co_u32_e64 v51, s[24:25], 0, v51, s[24:25]
	v_addc_co_u32_e64 v50, s[68:69], 0, v50, s[68:69]
	v_addc_co_u32_e32 v50, vcc, 0, v50, vcc
	v_cmp_eq_u32_e64 s[16:17], v8, v11
	v_cmp_eq_u32_e64 s[24:25], v7, v11
	v_cmp_eq_u32_e64 s[68:69], v12, v11
	v_cmp_eq_u32_e32 vcc, v2, v14
	v_addc_co_u32_e64 v50, s[16:17], 0, v50, s[16:17]
	v_addc_co_u32_e64 v50, s[24:25], 0, v50, s[24:25]
	v_addc_co_u32_e64 v50, s[68:69], 0, v50, s[68:69]
	v_addc_co_u32_e32 v49, vcc, 0, v49, vcc
	v_cmp_eq_u32_e64 s[16:17], v3, v14
	v_cmp_eq_u32_e64 s[24:25], v8, v14
	v_cmp_eq_u32_e64 s[68:69], v7, v14
	v_cmp_eq_u32_e32 vcc, v12, v14
	v_addc_co_u32_e64 v49, s[16:17], 0, v49, s[16:17]
	v_addc_co_u32_e64 v49, s[24:25], 0, v49, s[24:25]
	v_addc_co_u32_e64 v49, s[68:69], 0, v49, s[68:69]
	v_addc_co_u32_e32 v49, vcc, 0, v49, vcc
	v_cmp_eq_u32_e64 s[16:17], v11, v14
	v_cmp_eq_u32_e64 s[24:25], v2, v15
	v_cmp_eq_u32_e64 s[68:69], v3, v15
	v_cmp_eq_u32_e32 vcc, v8, v15
	v_addc_co_u32_e64 v49, s[16:17], 0, v49, s[16:17]
	v_addc_co_u32_e64 v48, s[24:25], 0, v48, s[24:25]
	v_addc_co_u32_e64 v48, s[68:69], 0, v48, s[68:69]
	v_addc_co_u32_e32 v48, vcc, 0, v48, vcc
	v_cmp_eq_u32_e64 s[16:17], v7, v15
	v_cmp_eq_u32_e64 s[24:25], v12, v15
	v_cmp_eq_u32_e64 s[68:69], v11, v15
	v_cmp_eq_u32_e32 vcc, v14, v15
	v_addc_co_u32_e64 v48, s[16:17], 0, v48, s[16:17]
	v_addc_co_u32_e64 v48, s[24:25], 0, v48, s[24:25]
	v_addc_co_u32_e64 v48, s[68:69], 0, v48, s[68:69]
	v_addc_co_u32_e32 v48, vcc, 0, v48, vcc
.Ltk_loop:
	s_add_i32 s65, s23, 1
	s_min_u32 s65, s65, s92
	v_lshl_add_u32 v56, s65, 2, v79
	ds_read_b32 v56, v56 offset:45056
	v_cmp_lt_u32_e32 vcc, s23, v0
	s_waitcnt lgkmcnt(1)
	s_nop 1
	v_addc_co_u32_e32 v81, vcc, 0, v80, vcc
	v_cmp_gt_i32_e64 s[16:17], v81, v2
	v_cmp_gt_i32_e64 s[24:25], v81, v3
	v_cmp_gt_i32_e64 s[68:69], v81, v8
	v_cmp_gt_i32_e32 vcc, v81, v7
	v_addc_co_u32_e64 v55, s[16:17], 0, v55, s[16:17]
	v_addc_co_u32_e64 v54, s[24:25], 0, v54, s[24:25]
	v_addc_co_u32_e64 v53, s[68:69], 0, v53, s[68:69]
	v_addc_co_u32_e32 v52, vcc, 0, v52, vcc
	v_cmp_gt_i32_e64 s[16:17], v81, v12
	v_cmp_gt_i32_e64 s[24:25], v81, v11
	v_cmp_gt_i32_e64 s[68:69], v81, v14
	v_cmp_gt_i32_e32 vcc, v81, v15
	v_addc_co_u32_e64 v51, s[16:17], 0, v51, s[16:17]
	v_addc_co_u32_e64 v50, s[24:25], 0, v50, s[24:25]
	v_addc_co_u32_e64 v49, s[68:69], 0, v49, s[68:69]
	v_addc_co_u32_e32 v48, vcc, 0, v48, vcc
	s_add_i32 s23, s23, 1
	s_cmp_lt_u32 s23, s22
	s_cbranch_scc0 .Ltk_done
	s_waitcnt lgkmcnt(0)
	v_mov_b32_e32 v80, v56
	s_branch .Ltk_loop
.Ltk_done:
	s_waitcnt lgkmcnt(0)
	s_branch .LBB0_1416
.LBB0_1380:
	s_mov_b64 s[10:11], s[8:9]
	s_and_b64 vcc, exec, s[44:45]
	s_mov_b64 s[8:9], s[10:11]
	s_cbranch_vccz .LBB0_1333
	s_branch .LBB0_1510
.LBB0_1416:
	v_cmp_gt_u32_e32 vcc, 16, v55
	s_and_b64 s[16:17], vcc, s[50:51]
	v_cmp_gt_u32_e32 vcc, 16, v54
	v_cndmask_b32_e64 v2, 0, 1, s[16:17]
	s_and_b64 s[16:17], vcc, s[48:49]
	v_cndmask_b32_e64 v3, 0, 2, s[16:17]
	v_or_b32_e32 v2, v3, v2
	v_cndmask_b32_e64 v3, 4, 0, s[54:55]
	v_cmp_gt_u32_e32 vcc, 16, v53
	v_cndmask_b32_e64 v4, 8, 0, s[52:53]
	v_xor_b32_e32 v5, 2, v221
	v_cndmask_b32_e32 v3, 0, v3, vcc
	v_cmp_gt_u32_e32 vcc, 16, v52
	s_nop 1
	v_cndmask_b32_e32 v4, 0, v4, vcc
	v_or3_b32 v2, v2, v3, v4
	v_cndmask_b32_e64 v3, 16, 0, s[58:59]
	v_cmp_gt_u32_e32 vcc, 16, v51
	v_cndmask_b32_e64 v4, 32, 0, s[56:57]
	s_nop 0
	v_cndmask_b32_e32 v3, 0, v3, vcc
	v_cmp_gt_u32_e32 vcc, 16, v50
	s_nop 1
	v_cndmask_b32_e32 v4, 0, v4, vcc
	v_or3_b32 v2, v2, v3, v4
	v_cndmask_b32_e64 v3, 64, 0, s[62:63]
	v_cmp_gt_u32_e32 vcc, 16, v49
	v_cndmask_b32_e64 v4, v226, 0, s[60:61]
	s_nop 0
	v_cndmask_b32_e32 v3, 0, v3, vcc
	v_cmp_gt_u32_e32 vcc, 16, v48
	s_nop 1
	v_cndmask_b32_e32 v4, 0, v4, vcc
	v_or3_b32 v2, v2, v3, v4
	v_xor_b32_e32 v4, 1, v221
	v_subrev_u32_e32 v3, 32, v0
	v_cmp_lt_i32_e32 vcc, v4, v107
	v_lshlrev_b32_e32 v0, v0, v2
	v_lshlrev_b32_e32 v2, v3, v2
	v_cndmask_b32_e32 v4, v221, v4, vcc
	v_cmp_lt_u32_e32 vcc, 3, v78
	v_lshlrev_b32_e32 v4, 2, v4
	s_nop 0
	v_cndmask_b32_e32 v2, 0, v2, vcc
	ds_bpermute_b32 v3, v4, v2
	v_cmp_gt_u32_e32 vcc, 4, v78
	s_waitcnt lgkmcnt(0)
	v_or_b32_e32 v2, v3, v2
	v_cndmask_b32_e32 v0, 0, v0, vcc
	ds_bpermute_b32 v4, v4, v0
	v_cmp_lt_i32_e32 vcc, v5, v107
	s_waitcnt lgkmcnt(0)
	v_or_b32_e32 v0, v4, v0
	v_cndmask_b32_e32 v5, v221, v5, vcc
	v_lshlrev_b32_e32 v5, 2, v5
	ds_bpermute_b32 v3, v5, v2
	ds_bpermute_b32 v4, v5, v0
	s_waitcnt lgkmcnt(1)
	v_or_b32_e32 v3, v3, v2
	v_xor_b32_e32 v2, 4, v221
	v_cmp_lt_i32_e32 vcc, v2, v107
	s_waitcnt lgkmcnt(0)
	v_or_b32_e32 v0, v4, v0
	v_cndmask_b32_e32 v2, v221, v2, vcc
	v_lshlrev_b32_e32 v4, 2, v2
	ds_bpermute_b32 v2, v4, v0
	ds_bpermute_b32 v4, v4, v3
	s_and_saveexec_b64 s[16:17], s[46:47]
	v_readlane_b32 s92, v254, 29
	v_readlane_b32 s93, v254, 30
	s_cbranch_execz .LBB0_1425
	v_add_u32_e32 v5, 0, v76
	s_mov_b64 s[46:47], exec
	v_add_u32_e32 v5, 0x1b400, v5
	s_waitcnt lgkmcnt(0)
	v_or_b32_e32 v3, v4, v3
	v_or_b32_e32 v0, v2, v0
	s_mov_b32 s22, 0
	ds_write2_b32 v5, v0, v3 offset1:1
